# layer-2 projection phase: work re-distributed between workgroups (the 32 that own a compression-GEMM tile take no projection tile; the other 224 walk the 320 projection tiles with stride 224; the idle
# baseline (speedup 1.0000x reference)
.LBB0_212:
	s_cmpk_lg_i32 s33, 0xe0
	s_cbranch_scc1 .Lp17_r
	s_movk_i32 s33, 0x100

.LBB0_252:
	v_writelane_b32 v254, s34, 25
	s_add_i32 s0, s21, s79
	s_ashr_i32 s1, s0, 31
	v_writelane_b32 v254, s35, 26
	s_abs_i32 s0, s0
	v_readlane_b32 s3, v254, 43
	s_mul_hi_u32 s3, s0, s3
	v_readlane_b32 s6, v254, 41
	s_mul_i32 s3, s3, s6
	s_sub_i32 s0, s0, s3
	s_sub_i32 s3, s0, s6
	s_cmp_ge_u32 s0, s6
	s_cselect_b32 s0, s3, s0
	s_sub_i32 s3, s0, s6
	s_cmp_ge_u32 s0, s6
	s_cselect_b32 s0, s3, s0
	s_xor_b32 s0, s0, s1
	s_sub_i32 s47, s0, s1
	v_readlane_b32 s0, v254, 22
	s_cmp_lg_u32 s0, 17
	s_cbranch_scc1 .Lp17_skip
	s_cmp_lg_u32 s75, 0
	s_cbranch_scc1 .Lp17_skip
	s_cmpk_lg_i32 s33, 0x100
	s_cbranch_scc1 .Lp17_skip
	s_movk_i32 s33, 0xe0
	s_cmp_lt_u32 s79, 64
	s_cbranch_scc1 .Lp17_skip
	s_sub_i32 s47, s79, 32
	s_cmp_ge_u32 s79, 0x60
	s_cbranch_scc1 .Lp17_skip
	s_movk_i32 s47, 0x140
.Lp17_skip:
	s_ashr_i32 s0, s95, 31
	s_lshr_b32 s0, s0, 24
	s_add_i32 s0, s95, s0
	s_ashr_i32 s40, s0, 8
	s_ashr_i32 s0, s27, 31
	s_lshr_b32 s0, s0, 24
	s_add_i32 s0, s27, s0
	s_ashr_i32 s92, s0, 8
	s_mul_i32 s0, s92, s40
	v_writelane_b32 v254, s0, 29
	s_ashr_i32 s29, s28, 31
	s_lshl_b64 s[64:65], s[28:29], 8
	v_writelane_b32 v254, s1, 30
	s_lshr_b32 s0, s29, 26
	s_add_i32 s0, s28, s0
	s_ashr_i32 s41, s0, 6
	s_lshl_b64 s[66:67], s[28:29], 9
	s_mov_b64 s[6:7], -1
	s_mov_b64 s[12:13], 0
	s_cmp_lt_i32 s23, 2
	s_mov_b64 s[0:1], 0
	s_cbranch_scc1 .LBB0_384
	s_cmp_gt_i32 s23, 2
	s_cbranch_scc0 .LBB0_323
	s_cmp_eq_u32 s23, 3
	s_mov_b64 s[0:1], -1
	s_cbranch_scc0 .LBB0_322
	s_mul_i32 s6, s92, s40
	s_cmp_lt_i32 s47, s6
	s_cselect_b64 s[0:1], -1, 0
	s_cmp_ge_i32 s47, s6
	v_readfirstlane_b32 s22, v162
	s_cbranch_scc1 .LBB0_261
	s_mul_i32 s6, s92, s40
	s_ashr_i32 s3, s6, 31
	s_lshr_b32 s3, s3, 29
	s_add_i32 s3, s6, s3
	s_ashr_i32 s11, s3, 3
	s_and_b32 s3, s3, -8
	s_sub_i32 s14, s6, s3
	s_ashr_i32 s3, s47, 31
	s_lshr_b32 s3, s3, 29
	s_add_i32 s3, s47, s3
	s_and_b32 s6, s3, -8
	s_sub_i32 s9, s47, s6
	s_add_i32 s10, s11, 1
	s_cmp_ge_i32 s9, s14
	s_mov_b64 s[6:7], -1
	s_cbranch_scc0 .LBB0_258
	s_sub_i32 s7, s9, s14
	s_mul_i32 s6, s10, s14
	s_mul_i32 s7, s7, s11
	s_add_i32 s8, s7, s6
	s_mov_b64 s[6:7], 0

.LBB0_276:
	s_add_u32 s3, s20, 0x100
	s_addc_u32 s34, s21, 0
	s_add_u32 s8, s30, 0x80
	v_mov_b64_e32 v[0:1], 0
	v_mov_b64_e32 v[2:3], 0
	v_mov_b64_e32 v[4:5], 0
	v_mov_b64_e32 v[6:7], 0
	v_mov_b64_e32 v[8:9], 0
	v_mov_b64_e32 v[10:11], 0
	v_mov_b64_e32 v[12:13], 0
	v_mov_b64_e32 v[14:15], 0
	v_mov_b64_e32 v[16:17], 0
	v_mov_b64_e32 v[18:19], 0
	v_mov_b64_e32 v[20:21], 0
	v_mov_b64_e32 v[22:23], 0
	v_mov_b64_e32 v[24:25], 0
	v_mov_b64_e32 v[26:27], 0
	v_mov_b64_e32 v[28:29], 0
	v_mov_b64_e32 v[30:31], 0
	v_mov_b64_e32 v[32:33], 0
	v_mov_b64_e32 v[34:35], 0
	v_mov_b64_e32 v[36:37], 0
	v_mov_b64_e32 v[38:39], 0
	v_mov_b64_e32 v[40:41], 0
	v_mov_b64_e32 v[42:43], 0
	v_mov_b64_e32 v[44:45], 0
	v_mov_b64_e32 v[46:47], 0
	v_mov_b64_e32 v[48:49], 0
	v_mov_b64_e32 v[50:51], 0
	v_mov_b64_e32 v[52:53], 0
	v_mov_b64_e32 v[54:55], 0
	v_mov_b64_e32 v[56:57], 0
	v_mov_b64_e32 v[58:59], 0
	v_mov_b64_e32 v[60:61], 0
	v_mov_b64_e32 v[62:63], 0
	v_mov_b64_e32 v[64:65], 0
	v_mov_b64_e32 v[66:67], 0
	v_mov_b64_e32 v[68:69], 0
	v_mov_b64_e32 v[70:71], 0
	v_mov_b64_e32 v[72:73], 0
	v_mov_b64_e32 v[74:75], 0
	v_mov_b64_e32 v[76:77], 0
	v_mov_b64_e32 v[78:79], 0
	v_mov_b64_e32 v[80:81], 0
	v_mov_b64_e32 v[82:83], 0
	v_mov_b64_e32 v[84:85], 0
	v_mov_b64_e32 v[86:87], 0
	v_mov_b64_e32 v[88:89], 0
	v_mov_b64_e32 v[90:91], 0
	v_mov_b64_e32 v[92:93], 0
	v_mov_b64_e32 v[94:95], 0
	v_mov_b64_e32 v[96:97], 0
	v_mov_b64_e32 v[98:99], 0
	v_mov_b64_e32 v[100:101], 0
	v_mov_b64_e32 v[102:103], 0
	v_mov_b64_e32 v[104:105], 0
	v_mov_b64_e32 v[106:107], 0
	v_mov_b64_e32 v[108:109], 0
	v_mov_b64_e32 v[110:111], 0
	v_mov_b64_e32 v[112:113], 0
	v_mov_b64_e32 v[114:115], 0
	v_mov_b64_e32 v[116:117], 0
	v_mov_b64_e32 v[118:119], 0
	v_mov_b64_e32 v[120:121], 0
	v_mov_b64_e32 v[122:123], 0
	v_mov_b64_e32 v[124:125], 0
	v_mov_b64_e32 v[126:127], 0
	s_addc_u32 s9, s31, 0
	s_mov_b32 s20, 0
	s_waitcnt vmcnt(0)
	s_nop 0
	s_nop 0
	s_nop 0
	s_nop 0
	s_nop 0
	s_nop 0
	s_nop 0
	s_nop 0
	s_nop 0
	s_nop 0
	s_nop 0
	s_nop 0
	s_nop 0
	s_nop 0
	s_nop 0
	s_nop 0
	s_nop 0
	s_nop 0
	s_nop 0
	s_nop 0
	s_nop 0
	s_nop 0
	s_nop 0
	s_nop 0
	s_nop 0
	s_nop 0
	s_nop 0
	s_nop 0
	s_nop 0
	s_nop 0
	s_nop 0
	s_nop 0
	s_nop 0
	s_nop 0
	s_nop 0
	s_nop 0
	s_nop 0
	s_nop 0
	s_nop 0
	s_nop 0
	s_nop 0
.LBB0_277:
	v_add_u32_e32 v150, s87, v171
	ds_read_b128 v[128:131], v150
	ds_read_b128 v[132:135], v150 offset:1024
	ds_read_b128 v[136:139], v150 offset:2048
	ds_read_b128 v[150:153], v150 offset:3072
	s_add_i32 s35, s20, 2
	s_add_u32 s30, s8, 0x80
	s_addc_u32 s21, s9, 0
	s_cmp_eq_u32 s38, s20
	s_cselect_b32 s20, s76, s30
	s_cselect_b32 s21, s77, s21
	s_cselect_b32 s31, s11, s34
	s_cselect_b32 s30, s10, s3
	v_lshl_add_u64 v[158:159], s[8:9], 0, v[148:149]
	s_add_i32 m0, s26, 0xc000
	ds_read_b128 v[154:157], v173
	ds_read_b128 v[166:169], v173 offset:1024
	ds_read_b128 v[174:177], v173 offset:2048
	ds_read_b128 v[178:181], v173 offset:3072
	ds_read_b128 v[182:185], v173 offset:4096
	ds_read_b128 v[186:189], v173 offset:5120
	ds_read_b128 v[190:193], v173 offset:6144
	ds_read_b128 v[194:197], v173 offset:7168
	global_load_lds_dwordx4 v[158:159], off
	v_lshl_add_u64 v[158:159], s[8:9], 0, v[146:147]
	s_add_i32 m0, s26, 0xe000
	s_nop 0
	global_load_lds_dwordx4 v[158:159], off
	s_waitcnt lgkmcnt(8)
	s_barrier
	s_waitcnt lgkmcnt(0)
	s_waitcnt lgkmcnt(0)
	v_mfma_f32_16x16x32_bf16 v[124:127], v[128:131], v[154:157], v[124:127]
	v_mfma_f32_16x16x32_bf16 v[120:123], v[136:139], v[154:157], v[120:123]
	v_mfma_f32_16x16x32_bf16 v[112:115], v[128:131], v[174:177], v[112:115]
	v_mfma_f32_16x16x32_bf16 v[108:111], v[136:139], v[174:177], v[108:111]
	v_mfma_f32_16x16x32_bf16 v[100:103], v[128:131], v[182:185], v[100:103]
	v_mfma_f32_16x16x32_bf16 v[92:95], v[136:139], v[182:185], v[92:95]
	v_mfma_f32_16x16x32_bf16 v[84:87], v[128:131], v[190:193], v[84:87]
	v_mfma_f32_16x16x32_bf16 v[76:79], v[136:139], v[190:193], v[76:79]
	v_mfma_f32_16x16x32_bf16 v[124:127], v[132:135], v[166:169], v[124:127]
	v_mfma_f32_16x16x32_bf16 v[120:123], v[150:153], v[166:169], v[120:123]
	v_mfma_f32_16x16x32_bf16 v[112:115], v[132:135], v[178:181], v[112:115]
	v_mfma_f32_16x16x32_bf16 v[108:111], v[150:153], v[178:181], v[108:111]
	v_mfma_f32_16x16x32_bf16 v[100:103], v[132:135], v[186:189], v[100:103]
	v_mfma_f32_16x16x32_bf16 v[92:95], v[150:153], v[186:189], v[92:95]
	v_mfma_f32_16x16x32_bf16 v[84:87], v[132:135], v[194:197], v[84:87]
	v_mfma_f32_16x16x32_bf16 v[76:79], v[150:153], v[194:197], v[76:79]
	s_barrier
	s_add_i32 s52, 0, 0x14000
	v_add_u32_e32 v158, s52, v171
	s_add_i32 s78, s87, s23
	ds_read_b128 v[198:201], v158
	ds_read_b128 v[232:235], v158 offset:1024
	ds_read_b128 v[236:239], v158 offset:2048
	ds_read_b128 v[240:243], v158 offset:3072
	v_lshl_add_u64 v[158:159], s[30:31], 0, v[160:161]
	s_mov_b32 m0, s78
	v_lshl_add_u64 v[202:203], s[30:31], 0, v[144:145]
	global_load_lds_dwordx4 v[158:159], off
	s_add_i32 m0, s78, 0x2000
	s_nop 0
	global_load_lds_dwordx4 v[202:203], off
	s_barrier
	s_waitcnt lgkmcnt(0)
	s_waitcnt lgkmcnt(0)
	v_mfma_f32_16x16x32_bf16 v[116:119], v[198:201], v[154:157], v[116:119]
	v_mfma_f32_16x16x32_bf16 v[104:107], v[236:239], v[154:157], v[104:107]
	v_mfma_f32_16x16x32_bf16 v[96:99], v[198:201], v[174:177], v[96:99]
	v_mfma_f32_16x16x32_bf16 v[88:91], v[236:239], v[174:177], v[88:91]
	v_mfma_f32_16x16x32_bf16 v[80:83], v[198:201], v[182:185], v[80:83]
	v_mfma_f32_16x16x32_bf16 v[72:75], v[236:239], v[182:185], v[72:75]
	v_mfma_f32_16x16x32_bf16 v[68:71], v[198:201], v[190:193], v[68:71]
	v_mfma_f32_16x16x32_bf16 v[64:67], v[236:239], v[190:193], v[64:67]
	v_mfma_f32_16x16x32_bf16 v[116:119], v[232:235], v[166:169], v[116:119]
	v_mfma_f32_16x16x32_bf16 v[104:107], v[240:243], v[166:169], v[104:107]
	v_mfma_f32_16x16x32_bf16 v[96:99], v[232:235], v[178:181], v[96:99]
	v_mfma_f32_16x16x32_bf16 v[88:91], v[240:243], v[178:181], v[88:91]
	v_mfma_f32_16x16x32_bf16 v[80:83], v[232:235], v[186:189], v[80:83]
	v_mfma_f32_16x16x32_bf16 v[72:75], v[240:243], v[186:189], v[72:75]
	v_mfma_f32_16x16x32_bf16 v[68:71], v[232:235], v[194:197], v[68:71]
	v_mfma_f32_16x16x32_bf16 v[64:67], v[240:243], v[194:197], v[64:67]
	s_mov_b32 m0, s26
	v_lshl_add_u64 v[206:207], s[20:21], 0, v[140:141]
	s_barrier
	ds_read_b128 v[154:157], v173 offset:16384
	ds_read_b128 v[166:169], v173 offset:17408
	ds_read_b128 v[174:177], v173 offset:18432
	ds_read_b128 v[178:181], v173 offset:19456
	ds_read_b128 v[182:185], v173 offset:20480
	ds_read_b128 v[186:189], v173 offset:21504
	ds_read_b128 v[190:193], v173 offset:22528
	ds_read_b128 v[194:197], v173 offset:23552
	global_load_lds_dwordx4 v[206:207], off
	v_lshl_add_u64 v[210:211], s[20:21], 0, v[142:143]
	s_mov_b32 m0, s16
	s_nop 0
	global_load_lds_dwordx4 v[210:211], off
	s_barrier
	s_waitcnt lgkmcnt(0)
	s_waitcnt lgkmcnt(0)
	v_mfma_f32_16x16x32_bf16 v[60:63], v[128:131], v[154:157], v[60:63]
	v_mfma_f32_16x16x32_bf16 v[56:59], v[136:139], v[154:157], v[56:59]
	v_mfma_f32_16x16x32_bf16 v[52:55], v[128:131], v[174:177], v[52:55]
	v_mfma_f32_16x16x32_bf16 v[44:47], v[136:139], v[174:177], v[44:47]
	v_mfma_f32_16x16x32_bf16 v[36:39], v[128:131], v[182:185], v[36:39]
	v_mfma_f32_16x16x32_bf16 v[28:31], v[136:139], v[182:185], v[28:31]
	v_mfma_f32_16x16x32_bf16 v[20:23], v[128:131], v[190:193], v[20:23]
	v_mfma_f32_16x16x32_bf16 v[12:15], v[136:139], v[190:193], v[12:15]
	v_mfma_f32_16x16x32_bf16 v[60:63], v[132:135], v[166:169], v[60:63]
	v_mfma_f32_16x16x32_bf16 v[56:59], v[150:153], v[166:169], v[56:59]
	v_mfma_f32_16x16x32_bf16 v[52:55], v[132:135], v[178:181], v[52:55]
	v_mfma_f32_16x16x32_bf16 v[44:47], v[150:153], v[178:181], v[44:47]
	v_mfma_f32_16x16x32_bf16 v[36:39], v[132:135], v[186:189], v[36:39]
	v_mfma_f32_16x16x32_bf16 v[28:31], v[150:153], v[186:189], v[28:31]
	v_mfma_f32_16x16x32_bf16 v[20:23], v[132:135], v[194:197], v[20:23]
	v_mfma_f32_16x16x32_bf16 v[12:15], v[150:153], v[194:197], v[12:15]
	s_barrier
	s_add_u32 s30, s30, s64
	s_addc_u32 s31, s31, s65
	s_add_i32 s52, s52, s23
	v_lshl_add_u64 v[244:245], s[30:31], 0, v[160:161]
	s_mov_b32 m0, s52
	v_lshl_add_u64 v[246:247], s[30:31], 0, v[144:145]
	global_load_lds_dwordx4 v[244:245], off
	s_add_i32 m0, s52, 0x2000
	s_nop 0
	global_load_lds_dwordx4 v[246:247], off
	s_waitcnt vmcnt(6)
	s_barrier
	v_mfma_f32_16x16x32_bf16 v[48:51], v[198:201], v[154:157], v[48:51]
	v_mfma_f32_16x16x32_bf16 v[40:43], v[236:239], v[154:157], v[40:43]
	v_mfma_f32_16x16x32_bf16 v[32:35], v[198:201], v[174:177], v[32:35]
	v_mfma_f32_16x16x32_bf16 v[24:27], v[236:239], v[174:177], v[24:27]
	v_mfma_f32_16x16x32_bf16 v[16:19], v[198:201], v[182:185], v[16:19]
	v_mfma_f32_16x16x32_bf16 v[8:11], v[236:239], v[182:185], v[8:11]
	v_mfma_f32_16x16x32_bf16 v[4:7], v[198:201], v[190:193], v[4:7]
	v_mfma_f32_16x16x32_bf16 v[0:3], v[236:239], v[190:193], v[0:3]
	v_mfma_f32_16x16x32_bf16 v[48:51], v[232:235], v[166:169], v[48:51]
	v_mfma_f32_16x16x32_bf16 v[40:43], v[240:243], v[166:169], v[40:43]
	v_mfma_f32_16x16x32_bf16 v[32:35], v[232:235], v[178:181], v[32:35]
	v_mfma_f32_16x16x32_bf16 v[24:27], v[240:243], v[178:181], v[24:27]
	v_mfma_f32_16x16x32_bf16 v[16:19], v[232:235], v[186:189], v[16:19]
	v_mfma_f32_16x16x32_bf16 v[8:11], v[240:243], v[186:189], v[8:11]
	v_mfma_f32_16x16x32_bf16 v[4:7], v[232:235], v[194:197], v[4:7]
	v_mfma_f32_16x16x32_bf16 v[0:3], v[240:243], v[194:197], v[0:3]
	s_add_i32 s30, 0, 0x18000
	v_add_u32_e32 v150, s30, v171
	s_barrier
	ds_read_b128 v[128:131], v150
	ds_read_b128 v[132:135], v150 offset:1024
	ds_read_b128 v[136:139], v150 offset:2048
	ds_read_b128 v[150:153], v150 offset:3072
	s_add_u32 s20, s20, s64
	s_addc_u32 s21, s21, s65
	s_mov_b32 m0, s17
	v_lshl_add_u64 v[198:199], s[20:21], 0, v[140:141]
	ds_read_b128 v[154:157], v173 offset:32768
	ds_read_b128 v[166:169], v173 offset:33792
	ds_read_b128 v[174:177], v173 offset:34816
	ds_read_b128 v[178:181], v173 offset:35840
	ds_read_b128 v[182:185], v173 offset:36864
	ds_read_b128 v[186:189], v173 offset:37888
	ds_read_b128 v[190:193], v173 offset:38912
	ds_read_b128 v[194:197], v173 offset:39936
	global_load_lds_dwordx4 v[198:199], off
	v_lshl_add_u64 v[198:199], s[20:21], 0, v[142:143]
	s_mov_b32 m0, s27
	s_nop 0
	global_load_lds_dwordx4 v[198:199], off
	s_waitcnt lgkmcnt(8)
	s_barrier
	s_waitcnt lgkmcnt(0)
	s_waitcnt lgkmcnt(0)
	v_mfma_f32_16x16x32_bf16 v[124:127], v[128:131], v[154:157], v[124:127]
	v_mfma_f32_16x16x32_bf16 v[120:123], v[136:139], v[154:157], v[120:123]
	v_mfma_f32_16x16x32_bf16 v[112:115], v[128:131], v[174:177], v[112:115]
	v_mfma_f32_16x16x32_bf16 v[108:111], v[136:139], v[174:177], v[108:111]
	v_mfma_f32_16x16x32_bf16 v[100:103], v[128:131], v[182:185], v[100:103]
	v_mfma_f32_16x16x32_bf16 v[92:95], v[136:139], v[182:185], v[92:95]
	v_mfma_f32_16x16x32_bf16 v[84:87], v[128:131], v[190:193], v[84:87]
	v_mfma_f32_16x16x32_bf16 v[76:79], v[136:139], v[190:193], v[76:79]
	v_mfma_f32_16x16x32_bf16 v[124:127], v[132:135], v[166:169], v[124:127]
	v_mfma_f32_16x16x32_bf16 v[120:123], v[150:153], v[166:169], v[120:123]
	v_mfma_f32_16x16x32_bf16 v[112:115], v[132:135], v[178:181], v[112:115]
	v_mfma_f32_16x16x32_bf16 v[108:111], v[150:153], v[178:181], v[108:111]
	v_mfma_f32_16x16x32_bf16 v[100:103], v[132:135], v[186:189], v[100:103]
	v_mfma_f32_16x16x32_bf16 v[92:95], v[150:153], v[186:189], v[92:95]
	v_mfma_f32_16x16x32_bf16 v[84:87], v[132:135], v[194:197], v[84:87]
	v_mfma_f32_16x16x32_bf16 v[76:79], v[150:153], v[194:197], v[76:79]
	s_barrier
	s_add_i32 s20, 0, 0x1c000
	s_add_i32 s21, s30, s23
	v_add_u32_e32 v240, s20, v171
	v_lshl_add_u64 v[158:159], v[158:159], 0, s[96:97]
	s_mov_b32 m0, s21
	ds_read_b128 v[198:201], v240
	ds_read_b128 v[232:235], v240 offset:1024
	ds_read_b128 v[236:239], v240 offset:2048
	ds_read_b128 v[240:243], v240 offset:3072
	global_load_lds_dwordx4 v[158:159], off
	v_lshl_add_u64 v[158:159], v[202:203], 0, s[96:97]
	s_add_i32 m0, s21, 0x2000
	s_nop 0
	global_load_lds_dwordx4 v[158:159], off
	s_barrier
	s_waitcnt lgkmcnt(0)
	s_waitcnt lgkmcnt(0)
	v_mfma_f32_16x16x32_bf16 v[116:119], v[198:201], v[154:157], v[116:119]
	v_mfma_f32_16x16x32_bf16 v[104:107], v[236:239], v[154:157], v[104:107]
	v_mfma_f32_16x16x32_bf16 v[96:99], v[198:201], v[174:177], v[96:99]
	v_mfma_f32_16x16x32_bf16 v[88:91], v[236:239], v[174:177], v[88:91]
	v_mfma_f32_16x16x32_bf16 v[80:83], v[198:201], v[182:185], v[80:83]
	v_mfma_f32_16x16x32_bf16 v[72:75], v[236:239], v[182:185], v[72:75]
	v_mfma_f32_16x16x32_bf16 v[68:71], v[198:201], v[190:193], v[68:71]
	v_mfma_f32_16x16x32_bf16 v[64:67], v[236:239], v[190:193], v[64:67]
	v_mfma_f32_16x16x32_bf16 v[116:119], v[232:235], v[166:169], v[116:119]
	v_mfma_f32_16x16x32_bf16 v[104:107], v[240:243], v[166:169], v[104:107]
	v_mfma_f32_16x16x32_bf16 v[96:99], v[232:235], v[178:181], v[96:99]
	v_mfma_f32_16x16x32_bf16 v[88:91], v[240:243], v[178:181], v[88:91]
	v_mfma_f32_16x16x32_bf16 v[80:83], v[232:235], v[186:189], v[80:83]
	v_mfma_f32_16x16x32_bf16 v[72:75], v[240:243], v[186:189], v[72:75]
	v_mfma_f32_16x16x32_bf16 v[68:71], v[232:235], v[194:197], v[68:71]
	v_mfma_f32_16x16x32_bf16 v[64:67], v[240:243], v[194:197], v[64:67]
	s_mov_b32 m0, s28
	v_lshl_add_u64 v[158:159], v[206:207], 0, s[96:97]
	s_barrier
	ds_read_b128 v[154:157], v173 offset:49152
	ds_read_b128 v[166:169], v173 offset:50176
	ds_read_b128 v[174:177], v173 offset:51200
	ds_read_b128 v[178:181], v173 offset:52224
	ds_read_b128 v[182:185], v173 offset:53248
	ds_read_b128 v[186:189], v173 offset:54272
	ds_read_b128 v[190:193], v173 offset:55296
	ds_read_b128 v[194:197], v173 offset:56320
	global_load_lds_dwordx4 v[158:159], off
	v_lshl_add_u64 v[158:159], v[210:211], 0, s[96:97]
	s_mov_b32 m0, s29
	s_nop 0
	global_load_lds_dwordx4 v[158:159], off
	s_barrier
	s_waitcnt lgkmcnt(0)
	s_waitcnt lgkmcnt(0)
	v_mfma_f32_16x16x32_bf16 v[60:63], v[128:131], v[154:157], v[60:63]
	v_mfma_f32_16x16x32_bf16 v[56:59], v[136:139], v[154:157], v[56:59]
	v_mfma_f32_16x16x32_bf16 v[52:55], v[128:131], v[174:177], v[52:55]
	v_mfma_f32_16x16x32_bf16 v[44:47], v[136:139], v[174:177], v[44:47]
	v_mfma_f32_16x16x32_bf16 v[36:39], v[128:131], v[182:185], v[36:39]
	v_mfma_f32_16x16x32_bf16 v[28:31], v[136:139], v[182:185], v[28:31]
	v_mfma_f32_16x16x32_bf16 v[20:23], v[128:131], v[190:193], v[20:23]
	v_mfma_f32_16x16x32_bf16 v[12:15], v[136:139], v[190:193], v[12:15]
	v_mfma_f32_16x16x32_bf16 v[60:63], v[132:135], v[166:169], v[60:63]
	v_mfma_f32_16x16x32_bf16 v[56:59], v[150:153], v[166:169], v[56:59]
	v_mfma_f32_16x16x32_bf16 v[52:55], v[132:135], v[178:181], v[52:55]
	v_mfma_f32_16x16x32_bf16 v[44:47], v[150:153], v[178:181], v[44:47]
	v_mfma_f32_16x16x32_bf16 v[36:39], v[132:135], v[186:189], v[36:39]
	v_mfma_f32_16x16x32_bf16 v[28:31], v[150:153], v[186:189], v[28:31]
	v_mfma_f32_16x16x32_bf16 v[20:23], v[132:135], v[194:197], v[20:23]
	v_mfma_f32_16x16x32_bf16 v[12:15], v[150:153], v[194:197], v[12:15]
	s_barrier
	s_add_i32 s20, s20, s23
	v_lshl_add_u64 v[128:129], v[244:245], 0, s[96:97]
	s_mov_b32 m0, s20
	s_nop 0
	global_load_lds_dwordx4 v[128:129], off
	v_lshl_add_u64 v[128:129], v[246:247], 0, s[96:97]
	s_add_i32 m0, s20, 0x2000
	s_nop 0
	global_load_lds_dwordx4 v[128:129], off
	s_waitcnt vmcnt(6)
	s_barrier
	v_mfma_f32_16x16x32_bf16 v[48:51], v[198:201], v[154:157], v[48:51]
	v_mfma_f32_16x16x32_bf16 v[40:43], v[236:239], v[154:157], v[40:43]
	v_mfma_f32_16x16x32_bf16 v[32:35], v[198:201], v[174:177], v[32:35]
	v_mfma_f32_16x16x32_bf16 v[24:27], v[236:239], v[174:177], v[24:27]
	v_mfma_f32_16x16x32_bf16 v[16:19], v[198:201], v[182:185], v[16:19]
	v_mfma_f32_16x16x32_bf16 v[8:11], v[236:239], v[182:185], v[8:11]
	v_mfma_f32_16x16x32_bf16 v[4:7], v[198:201], v[190:193], v[4:7]
	v_mfma_f32_16x16x32_bf16 v[0:3], v[236:239], v[190:193], v[0:3]
	v_mfma_f32_16x16x32_bf16 v[48:51], v[232:235], v[166:169], v[48:51]
	v_mfma_f32_16x16x32_bf16 v[40:43], v[240:243], v[166:169], v[40:43]
	v_mfma_f32_16x16x32_bf16 v[32:35], v[232:235], v[178:181], v[32:35]
	v_mfma_f32_16x16x32_bf16 v[24:27], v[240:243], v[178:181], v[24:27]
	v_mfma_f32_16x16x32_bf16 v[16:19], v[232:235], v[186:189], v[16:19]
	v_mfma_f32_16x16x32_bf16 v[8:11], v[240:243], v[186:189], v[8:11]
	v_mfma_f32_16x16x32_bf16 v[4:7], v[232:235], v[194:197], v[4:7]
	v_mfma_f32_16x16x32_bf16 v[0:3], v[240:243], v[194:197], v[0:3]
	s_add_u32 s3, s3, 0x100
	s_addc_u32 s34, s34, 0
	s_add_u32 s8, s8, 0x100
	s_addc_u32 s9, s9, 0
	s_cmp_ge_i32 s35, s41
	s_mov_b32 s20, s35
	s_barrier
	s_cbranch_scc0 .LBB0_277
	v_readlane_b32 s8, v254, 5
	v_mov_b32 v128, s8
	v_readlane_b32 s9, v254, 6
	v_readfirstlane_b32 s89, v128
	v_mov_b32 v128, s9
	s_add_u32 s3, s89, 0x14400000
	v_readfirstlane_b32 s90, v128
	s_addc_u32 s88, s90, 0
	s_add_u32 s8, s89, 0xc400000
	s_addc_u32 s9, s90, 0
	s_mov_b64 s[30:31], -1
	s_mov_b64 s[20:21], 0
	s_cmp_lt_i32 s2, 5
	s_mov_b64 s[78:79], 0
	s_mov_b64 s[82:83], 0
	s_cbranch_scc1 .LBB0_282
	s_mov_b64 s[82:83], -1
	s_mov_b64 s[30:31], 0
	s_cmp_gt_i32 s2, 5
	s_cbranch_scc0 .LBB0_282
	s_cmp_gt_i32 s2, 6
	s_cbranch_scc0 .LBB0_303
	s_cmp_eq_u32 s2, 7
	s_cselect_b64 s[82:83], -1, 0

.LBB0_758:
	s_cmp_lg_u32 s2, 3
	v_readlane_b32 s2, v254, 1
	s_cselect_b64 s[0:1], -1, 0
	v_readlane_b32 s3, v254, 2
	s_or_b64 s[0:1], s[0:1], s[2:3]
	s_and_b64 vcc, exec, s[0:1]
	s_cbranch_vccnz .LBB0_775
	s_cmpk_lg_i32 s33, 0x100
	s_cbranch_scc1 .Lp17w_skip
	s_movk_i32 s33, 0xe0
	s_cmp_ge_u32 s79, 0x80
	s_cbranch_scc0 .Lp17w_lo
	s_sub_i32 s79, s79, 32
	s_branch .Lp17w_skip
.Lp17w_lo:
	s_cmp_lt_u32 s79, 0x60
	s_cbranch_scc1 .Lp17w_skip
	s_mov_b32 s79, 0
.Lp17w_skip:
	s_cmpk_lt_i32 s33, 0x61
	s_cselect_b64 s[0:1], -1, 0
	s_cmpk_lt_i32 s79, 0x60
	s_cselect_b64 s[2:3], -1, 0
	s_or_b64 s[2:3], s[2:3], s[0:1]
	s_mov_b64 s[0:1], -1
	s_and_b64 vcc, exec, s[2:3]
	s_cbranch_vccz .LBB0_768
	s_cmpk_gt_i32 s33, 0x60
	s_cbranch_scc1 .LBB0_767
	v_readlane_b32 s0, v253, 22
	v_readlane_b32 s3, v253, 25
	v_readlane_b32 s8, v253, 30
	v_readlane_b32 s6, v253, 28
	v_readlane_b32 s7, v253, 29
	s_abs_i32 s3, s79
	v_readlane_b32 s8, v254, 43
	s_mul_hi_u32 s6, s3, s8
	v_readlane_b32 s7, v254, 41
	s_mul_i32 s6, s6, s7
	v_readlane_b32 s2, v253, 24
	s_sub_i32 s3, s3, s6
	s_ashr_i32 s2, s79, 31
	s_sub_i32 s6, s3, s7
	s_cmp_ge_u32 s3, s7
	s_cselect_b32 s3, s6, s3
	s_sub_i32 s6, s3, s7
	s_cmp_ge_u32 s3, s7
	s_cselect_b32 s3, s6, s3
	s_xor_b32 s3, s3, s2
	s_sub_i32 s2, s3, s2
	s_add_i32 s2, s2, s33
	s_ashr_i32 s3, s2, 31
	s_abs_i32 s2, s2
	s_mul_hi_u32 s6, s2, s8
	s_mul_i32 s6, s6, s7
	s_sub_i32 s2, s2, s6
	s_sub_i32 s6, s2, s7
	s_cmp_ge_u32 s2, s7
	s_cselect_b32 s2, s6, s2
	s_sub_i32 s6, s2, s7
	s_cmp_ge_u32 s2, s7
	s_waitcnt vmcnt(0) lgkmcnt(0)
	s_barrier
	v_readlane_b32 s12, v253, 34
	v_mov_b32 v0, s12
	s_cselect_b32 s2, s6, s2
	v_readlane_b32 s1, v253, 23
	v_readlane_b32 s13, v253, 35
	v_readfirstlane_b32 s0, v0
	v_mov_b32 v0, s13
	s_xor_b32 s12, s2, s3
	v_readlane_b32 s4, v253, 26
	v_readlane_b32 s5, v253, 27
	v_readlane_b32 s10, v253, 32
	v_readfirstlane_b32 s1, v0
	v_mov_b32 v0, s10
	v_ashrrev_i32_e32 v23, 4, v162
	s_sub_i32 s2, s12, s3
	v_readlane_b32 s11, v253, 33
	v_readfirstlane_b32 s4, v0
	v_mov_b32 v0, s11
	s_cmpk_gt_i32 s2, 0x2bf
	v_readfirstlane_b32 s5, v0
	v_mul_lo_u32 v1, v23, s34
	v_readlane_b32 s9, v253, 31
	v_readlane_b32 s14, v253, 36
	v_readlane_b32 s15, v253, 37
	s_cbranch_scc1 .LBB0_764
	s_add_u32 s0, s0, 0x2c00000
	s_addc_u32 s1, s1, 0
	s_add_u32 s6, s80, 0x7300000
	s_addc_u32 s7, s81, 0
	s_add_u32 s10, s4, 0x2000
	s_addc_u32 s11, s5, 0
	s_ashr_i32 s8, s2, 31
	s_lshr_b32 s8, s8, 29
	s_add_i32 s8, s2, s8
	s_ashr_i32 s13, s8, 3
	s_bfe_i32 s9, s13, 0x10001
	s_lshl_b32 s14, s13, 5
	s_lshl_b32 s8, s13, 6
	s_and_b32 s9, s9, 0xb00
	s_and_b32 s14, s14, 0xffffff80
	s_add_i32 s9, s9, s14
	s_and_b32 s8, s8, 64
	s_or_b32 s14, s9, s8
	s_cmp_eq_u64 s[4:5], 0
	s_cselect_b64 s[8:9], -1, 0
	s_and_b64 s[4:5], s[8:9], exec
	v_or_b32_e32 v2, s14, v163
	s_cselect_b32 s11, s1, s11
	s_cselect_b32 s10, s0, s10
	s_lshl_b32 s4, s13, 10
	s_lshl_b32 s5, s2, 7
	v_cmp_gt_i32_e32 vcc, s30, v2
	s_sub_i32 s4, s5, s4
	v_add_u32_e32 v6, s4, v23
	v_cndmask_b32_e32 v2, v209, v2, vcc
	v_ashrrev_i32_e32 v3, 31, v2
	v_add_u32_e32 v4, 0x60, v6
	v_lshl_add_u64 v[30:31], v[2:3], 2, s[0:1]
	v_mad_i64_i32 v[2:3], s[4:5], v4, s31, v[30:31]
	global_load_dwordx4 v[2:5], v[2:3], off
	v_ashrrev_i32_e32 v7, 31, v6
	v_lshl_add_u64 v[28:29], v[6:7], 2, s[10:11]
	global_load_dword v0, v[28:29], off offset:384
	v_lshl_add_u32 v9, v217, 4, 0
	s_lshl_b32 s3, s3, 7
	v_add_u32_e32 v9, v9, v1
	s_waitcnt vmcnt(1)
	v_cndmask_b32_e32 v11, 0, v3, vcc
	global_load_dword v3, v[28:29], off offset:256
	v_cndmask_b32_e32 v10, 0, v2, vcc
	v_add_u32_e32 v2, 64, v6
	v_cndmask_b32_e32 v5, 0, v5, vcc
	v_cndmask_b32_e32 v4, 0, v4, vcc
	s_waitcnt vmcnt(0)
	v_cndmask_b32_e64 v8, v3, 1.0, s[8:9]
	v_mad_i64_i32 v[2:3], s[4:5], v2, s31, v[30:31]
	global_load_dwordx4 v[14:17], v[2:3], off
	v_add_u32_e32 v2, 32, v6
	global_load_dword v3, v[28:29], off offset:128
	s_waitcnt vmcnt(1)
	v_cndmask_b32_e32 v12, 0, v16, vcc
	v_cndmask_b32_e32 v13, 0, v17, vcc
	s_waitcnt vmcnt(0)
	v_cndmask_b32_e64 v16, v3, 1.0, s[8:9]
	v_mad_i64_i32 v[2:3], s[4:5], v2, s31, v[30:31]
	global_load_dwordx4 v[24:27], v[2:3], off
	v_cndmask_b32_e32 v15, 0, v15, vcc
	global_load_dword v2, v[28:29], off
	v_cndmask_b32_e64 v0, v0, 1.0, s[8:9]
	v_cndmask_b32_e32 v14, 0, v14, vcc
	s_waitcnt vmcnt(1)
	v_cndmask_b32_e32 v19, 0, v27, vcc
	v_cndmask_b32_e32 v18, 0, v26, vcc
	s_waitcnt vmcnt(0)
	v_cndmask_b32_e64 v22, v2, 1.0, s[8:9]
	v_mad_i64_i32 v[2:3], s[4:5], v6, s31, v[30:31]
	global_load_dwordx4 v[26:29], v[2:3], off
	v_add_u32_e32 v6, 0x200, v162
	v_ashrrev_i32_e32 v3, 3, v162
	v_ashrrev_i32_e32 v7, 3, v6
	v_and_b32_e32 v2, -8, v3
	v_or_b32_e32 v3, 7, v3
	v_and_b32_e32 v6, -8, v7
	v_or_b32_e32 v7, 7, v7
	v_cndmask_b32_e32 v21, 0, v25, vcc
	v_cndmask_b32_e32 v20, 0, v24, vcc
	v_lshl_add_u32 v30, v216, 2, 0
	v_mul_lo_u32 v17, v2, s34
	v_mul_lo_u32 v31, v7, s34
	s_lshl_b32 s4, s12, 7
	v_ashrrev_i32_e32 v7, 31, v6
	s_sub_i32 s3, s4, s3
	s_lshl_b32 s12, s33, 7
	v_add_u32_e32 v17, v30, v17
	s_waitcnt vmcnt(0)
	v_cndmask_b32_e32 v25, 0, v29, vcc
	v_cndmask_b32_e32 v24, 0, v28, vcc
	v_mul_lo_u32 v28, v3, s34
	v_mul_lo_u32 v29, v6, s34
	v_cndmask_b32_e32 v27, 0, v27, vcc
	v_cndmask_b32_e32 v26, 0, v26, vcc
	v_ashrrev_i32_e32 v3, 31, v2
	v_add_u32_e32 v28, v30, v28
	v_add_u32_e32 v29, v30, v29
	v_add_u32_e32 v30, v30, v31

.Lp17w_r:
	v_readlane_b32 s79, v254, 7
	v_mov_b32_e32 v130, 1
	v_mov_b32_e32 v131, 0x42c
	s_branch .LBB0_818
